# P4 GLA decay stage hand-written: packed f32 FMAs for z, lean log-sigmoid, k/q loads issued first
# speedup vs baseline: 1.0045x; 1.0025x over previous
; #define LAS __attribute__((address_space(3)))
; template <int MODE, bool dry = false>
; __device__ __forceinline__ void gla_unit(const Args& a, LAS unsigned char* lds, int idx, int h, int tid, const float (&wu)[16], float bd) {
;     ...
;         for (int i = 0; i < TPT; ++i) { const size_t gi = (size_t)(row0 + tq * TPT + i) * 512 + col; kraw[i] = KB[gi]; qraw[i] = (MODE != 0) ? QB[gi] : (bf16_t)0; }
;         float bl[TPT]; float run = 0.f;
; #pragma unroll
;         for (int i = 0; i < TPT; ++i) { const LAS f32x4* dp = dlrL + (tq * TPT + i) * 4; float z = bd;
; #pragma unroll
;             for (int j4 = 0; j4 < 4; ++j4) { const f32x4 d = dp[j4]; z += d[0] * wu[4 * j4] + d[1] * wu[4 * j4 + 1] + d[2] * wu[4 * j4 + 2] + d[3] * wu[4 * j4 + 3]; }
;             const float la = (fminf(z, 0.f) - __logf(1.f + __expf(-fabsf(z)))) * (1.f / 16.f);
.LBB0_732:
	s_or_b64 exec, exec, s[6:7]
	s_lshr_b32 s9, s67, 7
	s_lshl_b32 s3, s9, 10
	s_add_i32 s3, s3, 0
	s_add_i32 s3, s3, 0x19800
	v_mov_b32_e32 v113, s3
	s_waitcnt lgkmcnt(0)
	s_barrier
	s_waitcnt vmcnt(12)
	v_mov_b32_e32 v117, v113
	s_and_b32 s3, s44, 0xffffffc
	s_add_i32 s3, s9, s3
	s_lshl_b32 s6, s3, 4
	s_ashr_i32 s7, s6, 31
	s_lshl_b64 s[10:11], s[6:7], 10
	s_and_b32 s3, s67, 0x3fffff80
	v_mov_b32_e32 v145, s11
	v_lshlrev_b32_e32 v113, 1, v71
	v_lshl_or_b32 v113, s66, 8, v113
	v_or_b32_e32 v144, s10, v113
	s_or_b32 s10, s6, 1
	s_ashr_i32 s11, s10, 31
	v_lshl_add_u64 v[150:151], s[30:31], 0, v[144:145]
	v_lshl_add_u64 v[144:145], s[26:27], 0, v[144:145]
	s_lshl_b64 s[10:11], s[10:11], 10
	global_load_ushort v186, v[150:151], off
	global_load_ushort v187, v[144:145], off
	v_or_b32_e32 v144, s10, v113
	s_or_b32 s10, s6, 2
	v_mov_b32_e32 v145, s11
	s_ashr_i32 s11, s10, 31
	v_lshl_add_u64 v[150:151], s[30:31], 0, v[144:145]
	v_lshl_add_u64 v[144:145], s[26:27], 0, v[144:145]
	s_lshl_b64 s[10:11], s[10:11], 10
	global_load_ushort v184, v[150:151], off
	global_load_ushort v183, v[144:145], off
	v_or_b32_e32 v144, s10, v113
	s_or_b32 s10, s6, 3
	v_mov_b32_e32 v145, s11
	s_ashr_i32 s11, s10, 31
	v_lshl_add_u64 v[150:151], s[30:31], 0, v[144:145]
	v_lshl_add_u64 v[144:145], s[26:27], 0, v[144:145]
	s_lshl_b64 s[10:11], s[10:11], 10
	global_load_ushort v182, v[150:151], off
	global_load_ushort v181, v[144:145], off
	v_or_b32_e32 v144, s10, v113
	s_or_b32 s10, s6, 4
	v_mov_b32_e32 v145, s11
	s_ashr_i32 s11, s10, 31
	v_lshl_add_u64 v[150:151], s[30:31], 0, v[144:145]
	v_lshl_add_u64 v[144:145], s[26:27], 0, v[144:145]
	s_lshl_b64 s[10:11], s[10:11], 10
	global_load_ushort v177, v[150:151], off
	global_load_ushort v175, v[144:145], off
	v_or_b32_e32 v144, s10, v113
	s_or_b32 s10, s6, 5
	v_mov_b32_e32 v145, s11
	s_ashr_i32 s11, s10, 31
	v_lshl_add_u64 v[150:151], s[30:31], 0, v[144:145]
	v_lshl_add_u64 v[144:145], s[26:27], 0, v[144:145]
	s_lshl_b64 s[10:11], s[10:11], 10
	global_load_ushort v174, v[150:151], off
	global_load_ushort v173, v[144:145], off
	v_or_b32_e32 v144, s10, v113
	s_or_b32 s10, s6, 6
	v_mov_b32_e32 v145, s11
	s_ashr_i32 s11, s10, 31
	v_lshl_add_u64 v[150:151], s[30:31], 0, v[144:145]
	v_lshl_add_u64 v[144:145], s[26:27], 0, v[144:145]
	s_lshl_b64 s[10:11], s[10:11], 10
	global_load_ushort v172, v[150:151], off
	global_load_ushort v170, v[144:145], off
	v_or_b32_e32 v144, s10, v113
	s_or_b32 s10, s6, 7
	v_mov_b32_e32 v145, s11
	s_ashr_i32 s11, s10, 31
	v_lshl_add_u64 v[150:151], s[30:31], 0, v[144:145]
	v_lshl_add_u64 v[144:145], s[26:27], 0, v[144:145]
	s_lshl_b64 s[10:11], s[10:11], 10
	global_load_ushort v168, v[150:151], off
	global_load_ushort v167, v[144:145], off
	v_or_b32_e32 v144, s10, v113
	s_or_b32 s10, s6, 8
	v_mov_b32_e32 v145, s11
	s_ashr_i32 s11, s10, 31
	v_lshl_add_u64 v[150:151], s[30:31], 0, v[144:145]
	v_lshl_add_u64 v[144:145], s[26:27], 0, v[144:145]
	s_lshl_b64 s[10:11], s[10:11], 10
	global_load_ushort v166, v[150:151], off
	global_load_ushort v165, v[144:145], off
	v_or_b32_e32 v144, s10, v113
	s_or_b32 s10, s6, 9
	v_mov_b32_e32 v145, s11
	s_ashr_i32 s11, s10, 31
	v_lshl_add_u64 v[150:151], s[30:31], 0, v[144:145]
	v_lshl_add_u64 v[144:145], s[26:27], 0, v[144:145]
	s_lshl_b64 s[10:11], s[10:11], 10
	global_load_ushort v163, v[150:151], off
	global_load_ushort v162, v[144:145], off
	v_or_b32_e32 v144, s10, v113
	s_or_b32 s10, s6, 10
	v_mov_b32_e32 v145, s11
	s_ashr_i32 s11, s10, 31
	v_lshl_add_u64 v[150:151], s[30:31], 0, v[144:145]
	v_lshl_add_u64 v[144:145], s[26:27], 0, v[144:145]
	s_lshl_b64 s[10:11], s[10:11], 10
	global_load_ushort v160, v[150:151], off
	global_load_ushort v159, v[144:145], off
	v_or_b32_e32 v144, s10, v113
	s_or_b32 s10, s6, 11
	v_mov_b32_e32 v145, s11
	s_ashr_i32 s11, s10, 31
	v_lshl_add_u64 v[150:151], s[30:31], 0, v[144:145]
	v_lshl_add_u64 v[144:145], s[26:27], 0, v[144:145]
	s_lshl_b64 s[10:11], s[10:11], 10
	global_load_ushort v158, v[150:151], off
	global_load_ushort v157, v[144:145], off
	v_or_b32_e32 v144, s10, v113
	s_or_b32 s10, s6, 12
	v_mov_b32_e32 v145, s11
	s_ashr_i32 s11, s10, 31
	v_lshl_add_u64 v[150:151], s[30:31], 0, v[144:145]
	v_lshl_add_u64 v[144:145], s[26:27], 0, v[144:145]
	s_lshl_b64 s[10:11], s[10:11], 10
	global_load_ushort v154, v[150:151], off
	global_load_ushort v153, v[144:145], off
	v_or_b32_e32 v144, s10, v113
	s_or_b32 s10, s6, 13
	v_mov_b32_e32 v145, s11
	s_ashr_i32 s11, s10, 31
	v_lshl_add_u64 v[150:151], s[30:31], 0, v[144:145]
	v_lshl_add_u64 v[144:145], s[26:27], 0, v[144:145]
	s_lshl_b64 s[10:11], s[10:11], 10
	global_load_ushort v152, v[150:151], off
	global_load_ushort v151, v[144:145], off
	v_or_b32_e32 v144, s10, v113
	s_or_b32 s10, s6, 14
	v_mov_b32_e32 v145, s11
	s_ashr_i32 s11, s10, 31
	v_lshl_add_u64 v[192:193], s[30:31], 0, v[144:145]
	v_lshl_add_u64 v[144:145], s[26:27], 0, v[144:145]
	s_lshl_b64 s[10:11], s[10:11], 10
	s_or_b32 s6, s6, 15
	global_load_ushort v150, v[192:193], off
	global_load_ushort v149, v[144:145], off
	v_or_b32_e32 v144, s10, v113
	v_mov_b32_e32 v145, s11
	s_ashr_i32 s7, s6, 31
	v_lshl_add_u64 v[192:193], s[30:31], 0, v[144:145]
	v_lshl_add_u64 v[144:145], s[26:27], 0, v[144:145]
	s_lshl_b64 s[6:7], s[6:7], 10
	global_load_ushort v146, v[192:193], off
	s_cmpk_lt_u32 s67, 0x80
	global_load_ushort v145, v[144:145], off
	v_or_b32_e32 v192, s6, v113
	v_mov_b32_e32 v193, s7
	v_lshl_add_u64 v[194:195], s[30:31], 0, v[192:193]
	v_lshl_add_u64 v[192:193], s[26:27], 0, v[192:193]
	global_load_ushort v144, v[194:195], off
	global_load_ushort v113, v[192:193], off
	ds_read_b128 v[118:121], v117
	ds_read_b128 v[122:125], v117 offset:16
	ds_read_b128 v[126:129], v117 offset:32
	ds_read_b128 v[130:133], v117 offset:48
	s_waitcnt lgkmcnt(0)
; #define LAS __attribute__((address_space(3)))
; template <int MODE, bool dry = false>
; __device__ __forceinline__ void gla_unit(const Args& a, LAS unsigned char* lds, int idx, int h, int tid, const float (&wu)[16], float bd) {
;     ...
;         for (int i = 0; i < TPT; ++i) { const LAS f32x4* dp = dlrL + (tq * TPT + i) * 4; float z = bd;
; #pragma unroll
;             for (int j4 = 0; j4 < 4; ++j4) { const f32x4 d = dp[j4]; z += d[0] * wu[4 * j4] + d[1] * wu[4 * j4 + 1] + d[2] * wu[4 * j4 + 2] + d[3] * wu[4 * j4 + 3]; }
;             const float la = (fminf(z, 0.f) - __logf(1.f + __expf(-fabsf(z)))) * (1.f / 16.f);
;             run += la; bl[i] = run; }
	v_pk_mul_f32 v[134:135], v[118:119], v[0:1]
	v_pk_mul_f32 v[140:141], v[120:121], v[2:3]
	v_pk_fma_f32 v[134:135], v[122:123], v[4:5], v[134:135]
	v_pk_fma_f32 v[140:141], v[124:125], v[6:7], v[140:141]
	v_pk_fma_f32 v[134:135], v[126:127], v[8:9], v[134:135]
	v_pk_fma_f32 v[140:141], v[128:129], v[10:11], v[140:141]
	v_pk_fma_f32 v[134:135], v[130:131], v[12:13], v[134:135]
	v_pk_fma_f32 v[140:141], v[132:133], v[14:15], v[140:141]
	ds_read_b128 v[118:121], v117 offset:64
	ds_read_b128 v[122:125], v117 offset:80
	ds_read_b128 v[126:129], v117 offset:96
	ds_read_b128 v[130:133], v117 offset:112
	v_pk_add_f32 v[134:135], v[134:135], v[140:141]
	v_add_f32_e32 v136, v134, v135
	v_add_f32_e32 v136, v74, v136
	v_mul_f32_e64 v137, |v136|, s60
	v_exp_f32_e32 v137, v137
	v_min_f32_e32 v138, 0, v136
	v_add_f32_e32 v137, 1.0, v137
	v_log_f32_e32 v137, v137
	s_nop 0
	v_fmamk_f32 v137, v137, 0xbf317218, v138
	v_mul_f32_e32 v116, 0x3d800000, v137
	s_waitcnt lgkmcnt(0)
	v_pk_mul_f32 v[134:135], v[118:119], v[0:1]
	v_pk_mul_f32 v[140:141], v[120:121], v[2:3]
	v_pk_fma_f32 v[134:135], v[122:123], v[4:5], v[134:135]
	v_pk_fma_f32 v[140:141], v[124:125], v[6:7], v[140:141]
	v_pk_fma_f32 v[134:135], v[126:127], v[8:9], v[134:135]
	v_pk_fma_f32 v[140:141], v[128:129], v[10:11], v[140:141]
	v_pk_fma_f32 v[134:135], v[130:131], v[12:13], v[134:135]
	v_pk_fma_f32 v[140:141], v[132:133], v[14:15], v[140:141]
	ds_read_b128 v[118:121], v117 offset:128
	ds_read_b128 v[122:125], v117 offset:144
	ds_read_b128 v[126:129], v117 offset:160
	ds_read_b128 v[130:133], v117 offset:176
	v_pk_add_f32 v[134:135], v[134:135], v[140:141]
	v_add_f32_e32 v136, v134, v135
	v_add_f32_e32 v136, v74, v136
	v_mul_f32_e64 v137, |v136|, s60
	v_exp_f32_e32 v137, v137
	v_min_f32_e32 v138, 0, v136
	v_add_f32_e32 v137, 1.0, v137
	v_log_f32_e32 v137, v137
	s_nop 0
	v_fmamk_f32 v137, v137, 0xbf317218, v138
	v_fmamk_f32 v115, v137, 0x3d800000, v116
	s_waitcnt lgkmcnt(0)
	v_pk_mul_f32 v[134:135], v[118:119], v[0:1]
	v_pk_mul_f32 v[140:141], v[120:121], v[2:3]
	v_pk_fma_f32 v[134:135], v[122:123], v[4:5], v[134:135]
	v_pk_fma_f32 v[140:141], v[124:125], v[6:7], v[140:141]
	v_pk_fma_f32 v[134:135], v[126:127], v[8:9], v[134:135]
	v_pk_fma_f32 v[140:141], v[128:129], v[10:11], v[140:141]
	v_pk_fma_f32 v[134:135], v[130:131], v[12:13], v[134:135]
	v_pk_fma_f32 v[140:141], v[132:133], v[14:15], v[140:141]
	ds_read_b128 v[118:121], v117 offset:192
	ds_read_b128 v[122:125], v117 offset:208
	ds_read_b128 v[126:129], v117 offset:224
	ds_read_b128 v[130:133], v117 offset:240
	v_pk_add_f32 v[134:135], v[134:135], v[140:141]
	v_add_f32_e32 v136, v134, v135
	v_add_f32_e32 v136, v74, v136
	v_mul_f32_e64 v137, |v136|, s60
	v_exp_f32_e32 v137, v137
	v_min_f32_e32 v138, 0, v136
	v_add_f32_e32 v137, 1.0, v137
	v_log_f32_e32 v137, v137
	s_nop 0
	v_fmamk_f32 v137, v137, 0xbf317218, v138
	v_fmamk_f32 v114, v137, 0x3d800000, v115
	s_waitcnt lgkmcnt(0)
	v_pk_mul_f32 v[134:135], v[118:119], v[0:1]
	v_pk_mul_f32 v[140:141], v[120:121], v[2:3]
	v_pk_fma_f32 v[134:135], v[122:123], v[4:5], v[134:135]
	v_pk_fma_f32 v[140:141], v[124:125], v[6:7], v[140:141]
	v_pk_fma_f32 v[134:135], v[126:127], v[8:9], v[134:135]
	v_pk_fma_f32 v[140:141], v[128:129], v[10:11], v[140:141]
	v_pk_fma_f32 v[134:135], v[130:131], v[12:13], v[134:135]
	v_pk_fma_f32 v[140:141], v[132:133], v[14:15], v[140:141]
	ds_read_b128 v[118:121], v117 offset:256
	ds_read_b128 v[122:125], v117 offset:272
	ds_read_b128 v[126:129], v117 offset:288
	ds_read_b128 v[130:133], v117 offset:304
	v_pk_add_f32 v[134:135], v[134:135], v[140:141]
	v_add_f32_e32 v136, v134, v135
	v_add_f32_e32 v136, v74, v136
	v_mul_f32_e64 v137, |v136|, s60
	v_exp_f32_e32 v137, v137
	v_min_f32_e32 v138, 0, v136
	v_add_f32_e32 v137, 1.0, v137
	v_log_f32_e32 v137, v137
	s_nop 0
	v_fmamk_f32 v137, v137, 0xbf317218, v138
	v_fmamk_f32 v112, v137, 0x3d800000, v114
	s_waitcnt lgkmcnt(0)
	v_pk_mul_f32 v[134:135], v[118:119], v[0:1]
	v_pk_mul_f32 v[140:141], v[120:121], v[2:3]
	v_pk_fma_f32 v[134:135], v[122:123], v[4:5], v[134:135]
	v_pk_fma_f32 v[140:141], v[124:125], v[6:7], v[140:141]
	v_pk_fma_f32 v[134:135], v[126:127], v[8:9], v[134:135]
	v_pk_fma_f32 v[140:141], v[128:129], v[10:11], v[140:141]
	v_pk_fma_f32 v[134:135], v[130:131], v[12:13], v[134:135]
	v_pk_fma_f32 v[140:141], v[132:133], v[14:15], v[140:141]
	ds_read_b128 v[118:121], v117 offset:320
	ds_read_b128 v[122:125], v117 offset:336
	ds_read_b128 v[126:129], v117 offset:352
	ds_read_b128 v[130:133], v117 offset:368
	v_pk_add_f32 v[134:135], v[134:135], v[140:141]
	v_add_f32_e32 v136, v134, v135
	v_add_f32_e32 v136, v74, v136
	v_mul_f32_e64 v137, |v136|, s60
	v_exp_f32_e32 v137, v137
	v_min_f32_e32 v138, 0, v136
	v_add_f32_e32 v137, 1.0, v137
	v_log_f32_e32 v137, v137
	s_nop 0
	v_fmamk_f32 v137, v137, 0xbf317218, v138
	v_fmamk_f32 v111, v137, 0x3d800000, v112
	s_waitcnt lgkmcnt(0)
	v_pk_mul_f32 v[134:135], v[118:119], v[0:1]
	v_pk_mul_f32 v[140:141], v[120:121], v[2:3]
	v_pk_fma_f32 v[134:135], v[122:123], v[4:5], v[134:135]
	v_pk_fma_f32 v[140:141], v[124:125], v[6:7], v[140:141]
	v_pk_fma_f32 v[134:135], v[126:127], v[8:9], v[134:135]
	v_pk_fma_f32 v[140:141], v[128:129], v[10:11], v[140:141]
	v_pk_fma_f32 v[134:135], v[130:131], v[12:13], v[134:135]
	v_pk_fma_f32 v[140:141], v[132:133], v[14:15], v[140:141]
	ds_read_b128 v[118:121], v117 offset:384
	ds_read_b128 v[122:125], v117 offset:400
	ds_read_b128 v[126:129], v117 offset:416
	ds_read_b128 v[130:133], v117 offset:432
	v_pk_add_f32 v[134:135], v[134:135], v[140:141]
	v_add_f32_e32 v136, v134, v135
	v_add_f32_e32 v136, v74, v136
	v_mul_f32_e64 v137, |v136|, s60
	v_exp_f32_e32 v137, v137
	v_min_f32_e32 v138, 0, v136
	v_add_f32_e32 v137, 1.0, v137
	v_log_f32_e32 v137, v137
	s_nop 0
	v_fmamk_f32 v137, v137, 0xbf317218, v138
	v_fmamk_f32 v110, v137, 0x3d800000, v111
	s_waitcnt lgkmcnt(0)
; #define LAS __attribute__((address_space(3)))
; template <int MODE, bool dry = false>
; __device__ __forceinline__ void gla_unit(const Args& a, LAS unsigned char* lds, int idx, int h, int tid, const float (&wu)[16], float bd) {
;     ...
;         for (int i = 0; i < TPT; ++i) { const LAS f32x4* dp = dlrL + (tq * TPT + i) * 4; float z = bd;
; #pragma unroll
;             for (int j4 = 0; j4 < 4; ++j4) { const f32x4 d = dp[j4]; z += d[0] * wu[4 * j4] + d[1] * wu[4 * j4 + 1] + d[2] * wu[4 * j4 + 2] + d[3] * wu[4 * j4 + 3]; }
;             const float la = (fminf(z, 0.f) - __logf(1.f + __expf(-fabsf(z)))) * (1.f / 16.f);
;             run += la; bl[i] = run; }
	v_pk_mul_f32 v[134:135], v[118:119], v[0:1]
	v_pk_mul_f32 v[140:141], v[120:121], v[2:3]
	v_pk_fma_f32 v[134:135], v[122:123], v[4:5], v[134:135]
	v_pk_fma_f32 v[140:141], v[124:125], v[6:7], v[140:141]
	v_pk_fma_f32 v[134:135], v[126:127], v[8:9], v[134:135]
	v_pk_fma_f32 v[140:141], v[128:129], v[10:11], v[140:141]
	v_pk_fma_f32 v[134:135], v[130:131], v[12:13], v[134:135]
	v_pk_fma_f32 v[140:141], v[132:133], v[14:15], v[140:141]
	ds_read_b128 v[118:121], v117 offset:448
	ds_read_b128 v[122:125], v117 offset:464
	ds_read_b128 v[126:129], v117 offset:480
	ds_read_b128 v[130:133], v117 offset:496
	v_pk_add_f32 v[134:135], v[134:135], v[140:141]
	v_add_f32_e32 v136, v134, v135
	v_add_f32_e32 v136, v74, v136
	v_mul_f32_e64 v137, |v136|, s60
	v_exp_f32_e32 v137, v137
	v_min_f32_e32 v138, 0, v136
	v_add_f32_e32 v137, 1.0, v137
	v_log_f32_e32 v137, v137
	s_nop 0
	v_fmamk_f32 v137, v137, 0xbf317218, v138
	v_fmamk_f32 v109, v137, 0x3d800000, v110
	s_waitcnt lgkmcnt(0)
	v_pk_mul_f32 v[134:135], v[118:119], v[0:1]
	v_pk_mul_f32 v[140:141], v[120:121], v[2:3]
	v_pk_fma_f32 v[134:135], v[122:123], v[4:5], v[134:135]
	v_pk_fma_f32 v[140:141], v[124:125], v[6:7], v[140:141]
	v_pk_fma_f32 v[134:135], v[126:127], v[8:9], v[134:135]
	v_pk_fma_f32 v[140:141], v[128:129], v[10:11], v[140:141]
	v_pk_fma_f32 v[134:135], v[130:131], v[12:13], v[134:135]
	v_pk_fma_f32 v[140:141], v[132:133], v[14:15], v[140:141]
	ds_read_b128 v[118:121], v117 offset:512
	ds_read_b128 v[122:125], v117 offset:528
	ds_read_b128 v[126:129], v117 offset:544
	ds_read_b128 v[130:133], v117 offset:560
	v_pk_add_f32 v[134:135], v[134:135], v[140:141]
	v_add_f32_e32 v136, v134, v135
	v_add_f32_e32 v136, v74, v136
	v_mul_f32_e64 v137, |v136|, s60
	v_exp_f32_e32 v137, v137
	v_min_f32_e32 v138, 0, v136
	v_add_f32_e32 v137, 1.0, v137
	v_log_f32_e32 v137, v137
	s_nop 0
	v_fmamk_f32 v137, v137, 0xbf317218, v138
	v_fmamk_f32 v108, v137, 0x3d800000, v109
	s_waitcnt lgkmcnt(0)
	v_pk_mul_f32 v[134:135], v[118:119], v[0:1]
	v_pk_mul_f32 v[140:141], v[120:121], v[2:3]
	v_pk_fma_f32 v[134:135], v[122:123], v[4:5], v[134:135]
	v_pk_fma_f32 v[140:141], v[124:125], v[6:7], v[140:141]
	v_pk_fma_f32 v[134:135], v[126:127], v[8:9], v[134:135]
	v_pk_fma_f32 v[140:141], v[128:129], v[10:11], v[140:141]
	v_pk_fma_f32 v[134:135], v[130:131], v[12:13], v[134:135]
	v_pk_fma_f32 v[140:141], v[132:133], v[14:15], v[140:141]
	ds_read_b128 v[118:121], v117 offset:576
	ds_read_b128 v[122:125], v117 offset:592
	ds_read_b128 v[126:129], v117 offset:608
	ds_read_b128 v[130:133], v117 offset:624
	v_pk_add_f32 v[134:135], v[134:135], v[140:141]
	v_add_f32_e32 v136, v134, v135
	v_add_f32_e32 v136, v74, v136
	v_mul_f32_e64 v137, |v136|, s60
	v_exp_f32_e32 v137, v137
	v_min_f32_e32 v138, 0, v136
	v_add_f32_e32 v137, 1.0, v137
	v_log_f32_e32 v137, v137
	s_nop 0
	v_fmamk_f32 v137, v137, 0xbf317218, v138
	v_fmamk_f32 v107, v137, 0x3d800000, v108
	s_waitcnt lgkmcnt(0)
	v_pk_mul_f32 v[134:135], v[118:119], v[0:1]
	v_pk_mul_f32 v[140:141], v[120:121], v[2:3]
	v_pk_fma_f32 v[134:135], v[122:123], v[4:5], v[134:135]
	v_pk_fma_f32 v[140:141], v[124:125], v[6:7], v[140:141]
	v_pk_fma_f32 v[134:135], v[126:127], v[8:9], v[134:135]
	v_pk_fma_f32 v[140:141], v[128:129], v[10:11], v[140:141]
	v_pk_fma_f32 v[134:135], v[130:131], v[12:13], v[134:135]
	v_pk_fma_f32 v[140:141], v[132:133], v[14:15], v[140:141]
	ds_read_b128 v[118:121], v117 offset:640
	ds_read_b128 v[122:125], v117 offset:656
	ds_read_b128 v[126:129], v117 offset:672
	ds_read_b128 v[130:133], v117 offset:688
	v_pk_add_f32 v[134:135], v[134:135], v[140:141]
	v_add_f32_e32 v136, v134, v135
	v_add_f32_e32 v136, v74, v136
	v_mul_f32_e64 v137, |v136|, s60
	v_exp_f32_e32 v137, v137
	v_min_f32_e32 v138, 0, v136
	v_add_f32_e32 v137, 1.0, v137
	v_log_f32_e32 v137, v137
	s_nop 0
	v_fmamk_f32 v137, v137, 0xbf317218, v138
	v_fmamk_f32 v106, v137, 0x3d800000, v107
	s_waitcnt lgkmcnt(0)
	v_pk_mul_f32 v[134:135], v[118:119], v[0:1]
	v_pk_mul_f32 v[140:141], v[120:121], v[2:3]
	v_pk_fma_f32 v[134:135], v[122:123], v[4:5], v[134:135]
	v_pk_fma_f32 v[140:141], v[124:125], v[6:7], v[140:141]
	v_pk_fma_f32 v[134:135], v[126:127], v[8:9], v[134:135]
	v_pk_fma_f32 v[140:141], v[128:129], v[10:11], v[140:141]
	v_pk_fma_f32 v[134:135], v[130:131], v[12:13], v[134:135]
	v_pk_fma_f32 v[140:141], v[132:133], v[14:15], v[140:141]
	ds_read_b128 v[118:121], v117 offset:704
	ds_read_b128 v[122:125], v117 offset:720
	ds_read_b128 v[126:129], v117 offset:736
	ds_read_b128 v[130:133], v117 offset:752
	v_pk_add_f32 v[134:135], v[134:135], v[140:141]
	v_add_f32_e32 v136, v134, v135
	v_add_f32_e32 v136, v74, v136
	v_mul_f32_e64 v137, |v136|, s60
	v_exp_f32_e32 v137, v137
	v_min_f32_e32 v138, 0, v136
	v_add_f32_e32 v137, 1.0, v137
	v_log_f32_e32 v137, v137
	s_nop 0
	v_fmamk_f32 v137, v137, 0xbf317218, v138
	v_fmamk_f32 v105, v137, 0x3d800000, v106
	s_waitcnt lgkmcnt(0)
; #define LAS __attribute__((address_space(3)))
; template <int MODE, bool dry = false>
; __device__ __forceinline__ void gla_unit(const Args& a, LAS unsigned char* lds, int idx, int h, int tid, const float (&wu)[16], float bd) {
;     ...
;         for (int i = 0; i < TPT; ++i) { const LAS f32x4* dp = dlrL + (tq * TPT + i) * 4; float z = bd;
; #pragma unroll
;             for (int j4 = 0; j4 < 4; ++j4) { const f32x4 d = dp[j4]; z += d[0] * wu[4 * j4] + d[1] * wu[4 * j4 + 1] + d[2] * wu[4 * j4 + 2] + d[3] * wu[4 * j4 + 3]; }
;             const float la = (fminf(z, 0.f) - __logf(1.f + __expf(-fabsf(z)))) * (1.f / 16.f);
;             run += la; bl[i] = run; }
;         psum[tq * 128 + dk] = run;
;         __syncthreads();
;         float off = 0.f, tot = 0.f;
; #pragma unroll
;         for (int p = 0; p < 4; ++p) { const float v = psum[p * 128 + dk]; tot += v; if (p < tq) off += v; }
;         if (tq == 0) { dvec[dk] = __expf(tot); if (MODE == 0) ((float*)((unsigned char*)a.out + Y_DEC))[(size_t)(idx * 4 + h) * 128 + dk] = __expf(tot); }
	v_pk_mul_f32 v[134:135], v[118:119], v[0:1]
	v_pk_mul_f32 v[140:141], v[120:121], v[2:3]
	v_pk_fma_f32 v[134:135], v[122:123], v[4:5], v[134:135]
	v_pk_fma_f32 v[140:141], v[124:125], v[6:7], v[140:141]
	v_pk_fma_f32 v[134:135], v[126:127], v[8:9], v[134:135]
	v_pk_fma_f32 v[140:141], v[128:129], v[10:11], v[140:141]
	v_pk_fma_f32 v[134:135], v[130:131], v[12:13], v[134:135]
	v_pk_fma_f32 v[140:141], v[132:133], v[14:15], v[140:141]
	ds_read_b128 v[118:121], v117 offset:768
	ds_read_b128 v[122:125], v117 offset:784
	ds_read_b128 v[126:129], v117 offset:800
	ds_read_b128 v[130:133], v117 offset:816
	v_pk_add_f32 v[134:135], v[134:135], v[140:141]
	v_add_f32_e32 v136, v134, v135
	v_add_f32_e32 v136, v74, v136
	v_mul_f32_e64 v137, |v136|, s60
	v_exp_f32_e32 v137, v137
	v_min_f32_e32 v138, 0, v136
	v_add_f32_e32 v137, 1.0, v137
	v_log_f32_e32 v137, v137
	s_nop 0
	v_fmamk_f32 v137, v137, 0xbf317218, v138
	v_fmamk_f32 v104, v137, 0x3d800000, v105
	s_waitcnt lgkmcnt(0)
	v_pk_mul_f32 v[134:135], v[118:119], v[0:1]
	v_pk_mul_f32 v[140:141], v[120:121], v[2:3]
	v_pk_fma_f32 v[134:135], v[122:123], v[4:5], v[134:135]
	v_pk_fma_f32 v[140:141], v[124:125], v[6:7], v[140:141]
	v_pk_fma_f32 v[134:135], v[126:127], v[8:9], v[134:135]
	v_pk_fma_f32 v[140:141], v[128:129], v[10:11], v[140:141]
	v_pk_fma_f32 v[134:135], v[130:131], v[12:13], v[134:135]
	v_pk_fma_f32 v[140:141], v[132:133], v[14:15], v[140:141]
	ds_read_b128 v[118:121], v117 offset:832
	ds_read_b128 v[122:125], v117 offset:848
	ds_read_b128 v[126:129], v117 offset:864
	ds_read_b128 v[130:133], v117 offset:880
	v_pk_add_f32 v[134:135], v[134:135], v[140:141]
	v_add_f32_e32 v136, v134, v135
	v_add_f32_e32 v136, v74, v136
	v_mul_f32_e64 v137, |v136|, s60
	v_exp_f32_e32 v137, v137
	v_min_f32_e32 v138, 0, v136
	v_add_f32_e32 v137, 1.0, v137
	v_log_f32_e32 v137, v137
	s_nop 0
	v_fmamk_f32 v137, v137, 0xbf317218, v138
	v_fmamk_f32 v103, v137, 0x3d800000, v104
	s_waitcnt lgkmcnt(0)
	v_pk_mul_f32 v[134:135], v[118:119], v[0:1]
	v_pk_mul_f32 v[140:141], v[120:121], v[2:3]
	v_pk_fma_f32 v[134:135], v[122:123], v[4:5], v[134:135]
	v_pk_fma_f32 v[140:141], v[124:125], v[6:7], v[140:141]
	v_pk_fma_f32 v[134:135], v[126:127], v[8:9], v[134:135]
	v_pk_fma_f32 v[140:141], v[128:129], v[10:11], v[140:141]
	v_pk_fma_f32 v[134:135], v[130:131], v[12:13], v[134:135]
	v_pk_fma_f32 v[140:141], v[132:133], v[14:15], v[140:141]
	ds_read_b128 v[118:121], v117 offset:896
	ds_read_b128 v[122:125], v117 offset:912
	ds_read_b128 v[126:129], v117 offset:928
	ds_read_b128 v[130:133], v117 offset:944
	v_pk_add_f32 v[134:135], v[134:135], v[140:141]
	v_add_f32_e32 v136, v134, v135
	v_add_f32_e32 v136, v74, v136
	v_mul_f32_e64 v137, |v136|, s60
	v_exp_f32_e32 v137, v137
	v_min_f32_e32 v138, 0, v136
	v_add_f32_e32 v137, 1.0, v137
	v_log_f32_e32 v137, v137
	s_nop 0
	v_fmamk_f32 v137, v137, 0xbf317218, v138
	v_fmamk_f32 v102, v137, 0x3d800000, v103
	s_waitcnt lgkmcnt(0)
	v_pk_mul_f32 v[134:135], v[118:119], v[0:1]
	v_pk_mul_f32 v[140:141], v[120:121], v[2:3]
	v_pk_fma_f32 v[134:135], v[122:123], v[4:5], v[134:135]
	v_pk_fma_f32 v[140:141], v[124:125], v[6:7], v[140:141]
	v_pk_fma_f32 v[134:135], v[126:127], v[8:9], v[134:135]
	v_pk_fma_f32 v[140:141], v[128:129], v[10:11], v[140:141]
	v_pk_fma_f32 v[134:135], v[130:131], v[12:13], v[134:135]
	v_pk_fma_f32 v[140:141], v[132:133], v[14:15], v[140:141]
	ds_read_b128 v[118:121], v117 offset:960
	ds_read_b128 v[122:125], v117 offset:976
	ds_read_b128 v[126:129], v117 offset:992
	ds_read_b128 v[130:133], v117 offset:1008
	v_pk_add_f32 v[134:135], v[134:135], v[140:141]
	v_add_f32_e32 v136, v134, v135
	v_add_f32_e32 v136, v74, v136
	v_mul_f32_e64 v137, |v136|, s60
	v_exp_f32_e32 v137, v137
	v_min_f32_e32 v138, 0, v136
	v_add_f32_e32 v137, 1.0, v137
	v_log_f32_e32 v137, v137
	s_nop 0
	v_fmamk_f32 v137, v137, 0xbf317218, v138
	v_fmamk_f32 v101, v137, 0x3d800000, v102
	s_waitcnt lgkmcnt(0)
	v_pk_mul_f32 v[134:135], v[118:119], v[0:1]
	v_pk_mul_f32 v[140:141], v[120:121], v[2:3]
	v_pk_fma_f32 v[134:135], v[122:123], v[4:5], v[134:135]
	v_pk_fma_f32 v[140:141], v[124:125], v[6:7], v[140:141]
	v_pk_fma_f32 v[134:135], v[126:127], v[8:9], v[134:135]
	v_pk_fma_f32 v[140:141], v[128:129], v[10:11], v[140:141]
	v_pk_fma_f32 v[134:135], v[130:131], v[12:13], v[134:135]
	v_pk_fma_f32 v[140:141], v[132:133], v[14:15], v[140:141]
	v_pk_add_f32 v[134:135], v[134:135], v[140:141]
	v_add_f32_e32 v136, v134, v135
	v_add_f32_e32 v136, v74, v136
	v_mul_f32_e64 v137, |v136|, s60
	v_exp_f32_e32 v137, v137
	v_min_f32_e32 v138, 0, v136
	v_add_f32_e32 v137, 1.0, v137
	v_log_f32_e32 v137, v137
	s_nop 0
	v_fmamk_f32 v137, v137, 0xbf317218, v138
	v_fmamk_f32 v73, v137, 0x3d800000, v101
	v_lshl_add_u32 v74, s3, 2, v78
	ds_write_b32 v74, v73
	s_waitcnt lgkmcnt(0)
	s_barrier
	ds_read2st64_b32 v[76:77], v78 offset1:2
	ds_read2st64_b32 v[74:75], v78 offset0:4 offset1:6
	s_cselect_b64 s[6:7], -1, 0
	s_cmpk_gt_u32 s67, 0x7f
	s_waitcnt lgkmcnt(1)
	v_add_f32_e32 v76, 0, v76
	s_cbranch_scc1 .LBB0_734
	v_add_f32_e32 v117, v76, v77
	s_waitcnt lgkmcnt(0)
	v_add_f32_e32 v117, v117, v74
	v_add_f32_e32 v117, v117, v75
	v_mul_f32_e32 v117, 0x3fb8aa3b, v117
	v_exp_f32_e32 v117, v117
	ds_write_b32 v82, v117
